# P10: final y stores write-through (sc1, 16 B) so the output is not left dirty in L2 for the end-of-kernel writeback
# speedup vs baseline: 1.0075x; 1.0047x over previous
.LBB0_1323:
	s_waitcnt vmcnt(21)
	v_lshlrev_b32_e32 v148, 16, v138
	v_and_b32_e32 v149, 0xffff0000, v138
	v_lshlrev_b32_e32 v138, 16, v139
	v_and_b32_e32 v139, 0xffff0000, v139
	v_mul_f32_e32 v150, v139, v139
	s_waitcnt vmcnt(20)
	v_lshlrev_b32_e32 v153, 16, v137
	v_lshlrev_b32_e32 v152, 16, v136
	v_and_b32_e32 v137, 0xffff0000, v137
	v_and_b32_e32 v136, 0xffff0000, v136
	s_waitcnt vmcnt(18)
	v_lshlrev_b32_e32 v159, 16, v132
	v_mul_f32_e32 v158, v149, v149
	v_pk_fma_f32 v[150:151], v[138:139], v[138:139], v[150:151] op_sel_hi:[1,1,0]
	v_pk_mul_f32 v[154:155], v[136:137], v[136:137]
	v_pk_fma_f32 v[162:163], v[148:149], v[148:149], v[158:159] op_sel_hi:[1,1,0]
	v_pk_fma_f32 v[154:155], v[152:153], v[152:153], v[154:155]
	v_and_b32_e32 v161, 0xffff0000, v132
	v_mov_b32_e32 v158, v162
	v_mov_b32_e32 v164, v150
	v_mov_b32_e32 v165, v159
	v_mul_f32_e32 v147, v161, v161
	v_pk_add_f32 v[150:151], v[162:163], v[150:151]
	v_pk_mul_f32 v[162:163], v[158:159], v[164:165]
	v_pk_add_f32 v[154:155], v[154:155], v[154:155] op_sel:[0,1] op_sel_hi:[1,0]
	v_lshlrev_b32_e32 v156, 16, v134
	v_and_b32_e32 v157, 0xffff0000, v134
	v_lshlrev_b32_e32 v134, 16, v135
	v_and_b32_e32 v135, 0xffff0000, v135
	v_mov_b32_e32 v151, v163
	v_mov_b32_e32 v155, v147
	v_lshlrev_b32_e32 v132, 16, v133
	v_and_b32_e32 v133, 0xffff0000, v133
	v_pk_add_f32 v[150:151], v[150:151], v[154:155]
	v_mul_f32_e32 v154, v157, v157
	v_mul_f32_e32 v158, v135, v135
	v_mul_f32_e32 v160, v132, v132
	v_mul_f32_e32 v166, v133, v133
	v_pk_fma_f32 v[154:155], v[156:157], v[156:157], v[154:155] op_sel_hi:[1,1,0]
	v_pk_fma_f32 v[162:163], v[134:135], v[134:135], v[158:159] op_sel_hi:[1,1,0]
	v_mov_b32_e32 v155, v160
	v_mov_b32_e32 v163, v166
	v_pk_add_f32 v[154:155], v[154:155], v[162:163]
	s_waitcnt vmcnt(7)
	v_lshlrev_b32_e32 v165, 16, v129
	v_pk_add_f32 v[150:151], v[150:151], v[154:155]
	v_lshlrev_b32_e32 v155, 16, v131
	v_lshlrev_b32_e32 v154, 16, v130
	v_and_b32_e32 v131, 0xffff0000, v131
	v_and_b32_e32 v130, 0xffff0000, v130
	v_pk_mul_f32 v[162:163], v[130:131], v[130:131]
	v_lshlrev_b32_e32 v164, 16, v128
	v_pk_fma_f32 v[162:163], v[154:155], v[154:155], v[162:163]
	v_and_b32_e32 v129, 0xffff0000, v129
	v_pk_add_f32 v[162:163], v[162:163], v[162:163] op_sel:[0,1] op_sel_hi:[1,0]
	v_and_b32_e32 v128, 0xffff0000, v128
	s_waitcnt vmcnt(5)
	v_lshlrev_b32_e32 v171, 16, v124
	v_pk_add_f32 v[150:151], v[150:151], v[150:151] op_sel:[0,1] op_sel_hi:[1,0]
	v_pk_mul_f32 v[166:167], v[128:129], v[128:129]
	v_mov_b32_e32 v170, v150
	v_mov_b32_e32 v174, v162
	v_mov_b32_e32 v175, v171
	v_pk_fma_f32 v[166:167], v[164:165], v[164:165], v[166:167]
	v_and_b32_e32 v173, 0xffff0000, v124
	v_pk_add_f32 v[150:151], v[150:151], v[162:163]
	v_pk_mul_f32 v[162:163], v[170:171], v[174:175]
	v_and_b32_e32 v169, 0xffff0000, v126
	v_mul_f32_e32 v147, v173, v173
	v_mov_b32_e32 v151, v163
	v_pk_add_f32 v[162:163], v[166:167], v[166:167] op_sel:[0,1] op_sel_hi:[1,0]
	v_lshlrev_b32_e32 v168, 16, v126
	v_lshlrev_b32_e32 v126, 16, v127
	v_and_b32_e32 v127, 0xffff0000, v127
	v_mov_b32_e32 v163, v147
	v_mul_f32_e32 v158, v169, v169
	v_lshlrev_b32_e32 v124, 16, v125
	v_and_b32_e32 v125, 0xffff0000, v125
	v_pk_add_f32 v[150:151], v[150:151], v[162:163]
	v_pk_fma_f32 v[162:163], v[168:169], v[168:169], v[158:159] op_sel_hi:[1,1,0]
	v_mul_f32_e32 v158, v127, v127
	v_mul_f32_e32 v160, v124, v124
	v_mul_f32_e32 v172, v125, v125
	v_pk_fma_f32 v[166:167], v[126:127], v[126:127], v[158:159] op_sel_hi:[1,1,0]
	v_mov_b32_e32 v163, v160
	v_mov_b32_e32 v167, v172
	v_pk_add_f32 v[162:163], v[162:163], v[166:167]
	v_mov_b32_e32 v160, v159
	v_pk_add_f32 v[150:151], v[150:151], v[162:163]
	v_lshlrev_b32_e32 v162, 16, v122
	v_add_f32_e32 v147, v150, v151
	ds_bpermute_b32 v150, v140, v147
	v_and_b32_e32 v163, 0xffff0000, v122
	v_lshlrev_b32_e32 v122, 16, v123
	v_and_b32_e32 v123, 0xffff0000, v123
	v_mov_b32_e32 v172, v171
	s_waitcnt lgkmcnt(0)
	v_add_f32_e32 v147, v147, v150
	ds_bpermute_b32 v150, v141, v147
	s_waitcnt lgkmcnt(0)
	v_add_f32_e32 v147, v147, v150
	ds_bpermute_b32 v150, v142, v147
	s_waitcnt lgkmcnt(0)
	v_add_f32_e32 v147, v147, v150
	ds_bpermute_b32 v150, v143, v147
	s_waitcnt lgkmcnt(0)
	v_add_f32_e32 v147, v147, v150
	ds_bpermute_b32 v150, v144, v147
	s_waitcnt lgkmcnt(0)
	v_add_f32_e32 v147, v147, v150
	ds_bpermute_b32 v150, v145, v147
	s_waitcnt lgkmcnt(0)
	v_add_f32_e32 v147, v147, v150
	v_fmamk_f32 v147, v147, 0x3a000000, v146
	v_mul_f32_e32 v150, 0x4b800000, v147
	v_cmp_gt_f32_e32 vcc, s17, v147
	s_nop 1
	v_cndmask_b32_e32 v147, v147, v150, vcc
	v_rsq_f32_e32 v147, v147
	s_nop 0
	v_mul_f32_e32 v150, 0x45800000, v147
	v_cndmask_b32_e32 v150, v147, v150, vcc
	v_pk_mul_f32 v[148:149], v[150:151], v[148:149] op_sel_hi:[0,1]
	v_pk_mul_f32 v[138:139], v[150:151], v[138:139] op_sel_hi:[0,1]
	v_pk_fma_f32 v[62:63], v[62:63], v[138:139], v[122:123]
	v_pk_fma_f32 v[60:61], v[60:61], v[148:149], v[162:163]
	global_store_dwordx4 v[72:73], v[60:63], off offset:-4096 sc1
	s_andn2_b64 vcc, exec, s[12:13]
	s_nop 0
	v_lshlrev_b32_e32 v60, 16, v120
	v_and_b32_e32 v61, 0xffff0000, v120
	v_lshlrev_b32_e32 v62, 16, v121
	v_and_b32_e32 v63, 0xffff0000, v121
	v_mov_b32_e32 v120, v152
	v_mov_b32_e32 v121, v136
	v_mov_b32_e32 v136, v153
	v_pk_mul_f32 v[120:121], v[150:151], v[120:121] op_sel_hi:[0,1]
	v_pk_mul_f32 v[122:123], v[150:151], v[136:137] op_sel_hi:[0,1]
	v_pk_fma_f32 v[58:59], v[58:59], v[122:123], v[62:63]
	v_pk_fma_f32 v[56:57], v[56:57], v[120:121], v[60:61]
	global_store_dwordx4 v[72:73], v[56:59], off offset:-3072 sc1
	v_pk_mul_f32 v[60:61], v[150:151], v[156:157] op_sel_hi:[0,1]
	v_pk_mul_f32 v[62:63], v[150:151], v[134:135] op_sel_hi:[0,1]
	v_lshlrev_b32_e32 v56, 16, v118
	v_and_b32_e32 v57, 0xffff0000, v118
	v_lshlrev_b32_e32 v58, 16, v119
	v_and_b32_e32 v59, 0xffff0000, v119
	v_pk_fma_f32 v[54:55], v[54:55], v[62:63], v[58:59]
	v_pk_fma_f32 v[52:53], v[52:53], v[60:61], v[56:57]
	global_store_dwordx4 v[72:73], v[52:55], off offset:-2048 sc1
	v_pk_mul_f32 v[56:57], v[160:161], v[150:151] op_sel_hi:[1,0]
	v_pk_mul_f32 v[58:59], v[132:133], v[150:151] op_sel_hi:[1,0]
	v_lshlrev_b32_e32 v52, 16, v116
	v_and_b32_e32 v53, 0xffff0000, v116
	v_lshlrev_b32_e32 v54, 16, v117
	v_and_b32_e32 v55, 0xffff0000, v117
	v_pk_fma_f32 v[50:51], v[50:51], v[58:59], v[54:55]
	v_pk_fma_f32 v[48:49], v[48:49], v[56:57], v[52:53]
	v_mov_b32_e32 v52, v154
	v_mov_b32_e32 v53, v130
	v_mov_b32_e32 v130, v155
	global_store_dwordx4 v[72:73], v[48:51], off offset:-1024 sc1
	v_pk_mul_f32 v[52:53], v[150:151], v[52:53] op_sel_hi:[0,1]
	v_pk_mul_f32 v[54:55], v[150:151], v[130:131] op_sel_hi:[0,1]
	s_waitcnt vmcnt(8)
	v_lshlrev_b32_e32 v48, 16, v114
	v_and_b32_e32 v49, 0xffff0000, v114
	v_lshlrev_b32_e32 v50, 16, v115
	v_and_b32_e32 v51, 0xffff0000, v115
	v_pk_fma_f32 v[46:47], v[46:47], v[54:55], v[50:51]
	v_pk_fma_f32 v[44:45], v[44:45], v[52:53], v[48:49]
	v_mov_b32_e32 v48, v164
	v_mov_b32_e32 v49, v128
	v_mov_b32_e32 v128, v165
	global_store_dwordx4 v[72:73], v[44:47], off sc1
	v_pk_mul_f32 v[48:49], v[150:151], v[48:49] op_sel_hi:[0,1]
	v_pk_mul_f32 v[50:51], v[150:151], v[128:129] op_sel_hi:[0,1]
	s_waitcnt vmcnt(8)
	v_lshlrev_b32_e32 v44, 16, v112
	v_and_b32_e32 v45, 0xffff0000, v112
	v_lshlrev_b32_e32 v46, 16, v113
	v_and_b32_e32 v47, 0xffff0000, v113
	v_pk_fma_f32 v[42:43], v[42:43], v[50:51], v[46:47]
	v_pk_fma_f32 v[40:41], v[40:41], v[48:49], v[44:45]
	global_store_dwordx4 v[72:73], v[40:43], off offset:1024 sc1
	v_pk_mul_f32 v[44:45], v[150:151], v[168:169] op_sel_hi:[0,1]
	v_pk_mul_f32 v[46:47], v[150:151], v[126:127] op_sel_hi:[0,1]
	s_waitcnt vmcnt(8)
	v_lshlrev_b32_e32 v40, 16, v110
	v_and_b32_e32 v41, 0xffff0000, v110
	v_lshlrev_b32_e32 v42, 16, v111
	v_and_b32_e32 v43, 0xffff0000, v111
	v_pk_fma_f32 v[38:39], v[38:39], v[46:47], v[42:43]
	v_pk_fma_f32 v[36:37], v[36:37], v[44:45], v[40:41]
	global_store_dwordx4 v[72:73], v[36:39], off offset:2048 sc1
	v_pk_mul_f32 v[40:41], v[172:173], v[150:151] op_sel_hi:[1,0]
	v_pk_mul_f32 v[42:43], v[124:125], v[150:151] op_sel_hi:[1,0]
	s_waitcnt vmcnt(8)
	v_lshlrev_b32_e32 v36, 16, v108
	v_and_b32_e32 v37, 0xffff0000, v108
	v_lshlrev_b32_e32 v38, 16, v109
	v_and_b32_e32 v39, 0xffff0000, v109
	s_waitcnt vmcnt(7)
	v_pk_fma_f32 v[34:35], v[34:35], v[42:43], v[38:39]
	v_pk_fma_f32 v[32:33], v[32:33], v[40:41], v[36:37]
	global_store_dwordx4 v[72:73], v[32:35], off offset:3072 sc1
	s_cbranch_vccnz .LBB0_1320
	v_and_b32_e32 v39, 0xffff0000, v82
	v_and_b32_e32 v38, 0xffff0000, v80
	v_and_b32_e32 v43, 0xffff0000, v83
	v_and_b32_e32 v42, 0xffff0000, v81
	v_lshlrev_b32_e32 v37, 16, v82
	v_lshlrev_b32_e32 v36, 16, v80
	v_lshlrev_b32_e32 v41, 16, v83
	v_lshlrev_b32_e32 v40, 16, v81
	v_pk_mul_f32 v[32:33], v[38:39], v[38:39]
	v_pk_mul_f32 v[34:35], v[42:43], v[42:43]
	v_pk_fma_f32 v[32:33], v[36:37], v[36:37], v[32:33]
	v_pk_fma_f32 v[34:35], v[40:41], v[40:41], v[34:35]
	v_and_b32_e32 v47, 0xffff0000, v79
	v_pk_add_f32 v[32:33], v[32:33], v[34:35]
	v_and_b32_e32 v46, 0xffff0000, v78
	v_pk_add_f32 v[32:33], v[32:33], v[32:33] op_sel_hi:[0,1]
	v_lshlrev_b32_e32 v45, 16, v79
	v_lshlrev_b32_e32 v44, 16, v78
	v_pk_mul_f32 v[34:35], v[46:47], v[46:47]
	v_lshlrev_b32_e32 v48, 16, v76
	v_and_b32_e32 v49, 0xffff0000, v76
	v_lshlrev_b32_e32 v54, 16, v77
	v_lshlrev_b32_e32 v50, 16, v96
	v_pk_fma_f32 v[34:35], v[44:45], v[44:45], v[34:35]
	v_mul_f32_e32 v51, v48, v48
	v_mul_f32_e32 v53, v49, v49
	v_and_b32_e32 v55, 0xffff0000, v77
	v_mul_f32_e32 v32, v54, v54
	v_mov_b32_e32 v52, v50
	v_pk_add_f32 v[34:35], v[34:35], v[34:35] op_sel_hi:[0,1]
	v_pk_fma_f32 v[56:57], v[54:55], v[54:55], v[32:33] op_sel_hi:[1,1,0]
	v_and_b32_e32 v120, 0xffff0000, v96
	v_lshlrev_b32_e32 v58, 16, v97
	v_and_b32_e32 v59, 0xffff0000, v97
	v_pk_add_f32 v[52:53], v[50:51], v[52:53]
	v_mul_f32_e32 v56, v120, v120
	v_mul_f32_e32 v34, v58, v58
	v_mul_f32_e32 v32, v59, v59
	v_mul_f32_e32 v60, v50, v50
	v_mov_b32_e32 v61, v53
	v_pk_add_f32 v[52:53], v[60:61], v[56:57]
	v_pk_add_f32 v[32:33], v[34:35], v[32:33]
	v_and_b32_e32 v57, 0xffff0000, v95
	v_pk_add_f32 v[32:33], v[52:53], v[32:33]
	v_and_b32_e32 v56, 0xffff0000, v94
	v_pk_add_f32 v[32:33], v[32:33], v[32:33] op_sel_hi:[0,1]
	v_lshlrev_b32_e32 v53, 16, v95
	v_lshlrev_b32_e32 v52, 16, v94
	v_pk_mul_f32 v[34:35], v[56:57], v[56:57]
	v_lshlrev_b32_e32 v60, 16, v92
	v_and_b32_e32 v61, 0xffff0000, v92
	v_lshlrev_b32_e32 v110, 16, v93
	v_lshlrev_b32_e32 v62, 16, v98
	v_pk_fma_f32 v[34:35], v[52:53], v[52:53], v[34:35]
	v_mul_f32_e32 v63, v60, v60
	v_mul_f32_e32 v109, v61, v61
	v_and_b32_e32 v111, 0xffff0000, v93
	v_mul_f32_e32 v32, v110, v110
	v_mov_b32_e32 v108, v62
	v_pk_add_f32 v[34:35], v[34:35], v[34:35] op_sel_hi:[0,1]
	v_pk_fma_f32 v[112:113], v[110:111], v[110:111], v[32:33] op_sel_hi:[1,1,0]
	v_and_b32_e32 v121, 0xffff0000, v98
	v_lshlrev_b32_e32 v114, 16, v99
	v_and_b32_e32 v115, 0xffff0000, v99
	v_pk_add_f32 v[108:109], v[62:63], v[108:109]
	v_mul_f32_e32 v112, v121, v121
	v_mul_f32_e32 v34, v114, v114
	v_mul_f32_e32 v32, v115, v115
	v_mul_f32_e32 v116, v62, v62
	v_mov_b32_e32 v117, v109
	v_pk_add_f32 v[108:109], v[116:117], v[112:113]
	v_pk_add_f32 v[32:33], v[34:35], v[32:33]
	s_ashr_i32 s11, s10, 31
	v_pk_add_f32 v[32:33], v[108:109], v[32:33]
	v_mov_b32_e32 v116, v37
	v_add_f32_e32 v32, v32, v33
	ds_bpermute_b32 v33, v140, v32
	v_mov_b32_e32 v117, v39
	v_mov_b32_e32 v118, v41
	v_mov_b32_e32 v119, v43
	s_lshl_b64 s[10:11], s[10:11], 13
	s_waitcnt lgkmcnt(0)
	v_add_f32_e32 v32, v32, v33
	ds_bpermute_b32 v33, v141, v32
	v_lshlrev_b32_e32 v34, 16, v91
	v_and_b32_e32 v35, 0xffff0000, v91
	v_lshl_add_u64 v[108:109], v[70:71], 0, s[10:11]
	v_mov_b32_e32 v37, v38
	s_waitcnt lgkmcnt(0)
	v_add_f32_e32 v32, v32, v33
	ds_bpermute_b32 v33, v142, v32
	v_mov_b32_e32 v41, v42
	v_mov_b32_e32 v51, v120
	v_mov_b32_e32 v63, v121
	s_waitcnt lgkmcnt(0)
	v_add_f32_e32 v32, v32, v33
	ds_bpermute_b32 v33, v143, v32
	s_waitcnt lgkmcnt(0)
	v_add_f32_e32 v32, v32, v33
	ds_bpermute_b32 v33, v144, v32
	s_waitcnt lgkmcnt(0)
	v_add_f32_e32 v32, v32, v33
	ds_bpermute_b32 v33, v145, v32
	s_waitcnt lgkmcnt(0)
	v_add_f32_e32 v32, v32, v33
	v_fmamk_f32 v32, v32, 0x3a000000, v146
	v_mul_f32_e32 v33, 0x4b800000, v32
	v_cmp_gt_f32_e32 vcc, s17, v32
	s_nop 1
	v_cndmask_b32_e32 v32, v32, v33, vcc
	v_rsq_f32_e32 v32, v32
	s_nop 0
	v_mul_f32_e32 v33, 0x45800000, v32
	v_cndmask_b32_e32 v112, v32, v33, vcc
	v_lshlrev_b32_e32 v32, 16, v90
	v_and_b32_e32 v33, 0xffff0000, v90
	v_pk_mul_f32 v[116:117], v[116:117], v[112:113] op_sel_hi:[1,0]
	v_pk_mul_f32 v[118:119], v[118:119], v[112:113] op_sel_hi:[1,0]
	v_pk_fma_f32 v[32:33], v[12:13], v[116:117], v[32:33]
	v_pk_fma_f32 v[34:35], v[14:15], v[118:119], v[34:35]
	global_store_dwordx4 v[108:109], v[32:35], off sc1
	v_pk_mul_f32 v[36:37], v[36:37], v[112:113] op_sel_hi:[1,0]
	v_pk_mul_f32 v[38:39], v[40:41], v[112:113] op_sel_hi:[1,0]
	v_lshlrev_b32_e32 v32, 16, v88
	v_and_b32_e32 v33, 0xffff0000, v88
	v_lshlrev_b32_e32 v34, 16, v89
	v_and_b32_e32 v35, 0xffff0000, v89
	v_pk_fma_f32 v[34:35], v[2:3], v[38:39], v[34:35]
	v_pk_fma_f32 v[32:33], v[0:1], v[36:37], v[32:33]
	v_mov_b32_e32 v36, v44
	v_mov_b32_e32 v37, v46
	v_mov_b32_e32 v46, v45
	global_store_dwordx4 v[108:109], v[32:35], off offset:1024 sc1
	v_pk_mul_f32 v[36:37], v[112:113], v[36:37] op_sel_hi:[0,1]
	v_pk_mul_f32 v[38:39], v[112:113], v[46:47] op_sel_hi:[0,1]
	v_lshlrev_b32_e32 v32, 16, v86
	v_and_b32_e32 v33, 0xffff0000, v86
	v_lshlrev_b32_e32 v34, 16, v87
	v_and_b32_e32 v35, 0xffff0000, v87
	v_pk_fma_f32 v[34:35], v[6:7], v[38:39], v[34:35]
	v_pk_fma_f32 v[32:33], v[4:5], v[36:37], v[32:33]
	global_store_dwordx4 v[108:109], v[32:35], off offset:2048 sc1
	v_pk_mul_f32 v[36:37], v[48:49], v[112:113] op_sel_hi:[1,0]
	v_pk_mul_f32 v[38:39], v[54:55], v[112:113] op_sel_hi:[1,0]
	v_lshlrev_b32_e32 v32, 16, v84
	v_and_b32_e32 v33, 0xffff0000, v84
	v_lshlrev_b32_e32 v34, 16, v85
	v_and_b32_e32 v35, 0xffff0000, v85
	v_pk_fma_f32 v[34:35], v[10:11], v[38:39], v[34:35]
	v_pk_fma_f32 v[32:33], v[8:9], v[36:37], v[32:33]
	global_store_dwordx4 v[108:109], v[32:35], off offset:3072 sc1
	v_pk_mul_f32 v[36:37], v[50:51], v[112:113] op_sel_hi:[1,0]
	v_pk_mul_f32 v[38:39], v[58:59], v[112:113] op_sel_hi:[1,0]
	v_lshlrev_b32_e32 v32, 16, v106
	v_and_b32_e32 v33, 0xffff0000, v106
	v_lshlrev_b32_e32 v34, 16, v107
	v_and_b32_e32 v35, 0xffff0000, v107
	v_pk_fma_f32 v[32:33], v[16:17], v[36:37], v[32:33]
	v_add_co_u32_e32 v36, vcc, s18, v108
	v_pk_fma_f32 v[34:35], v[18:19], v[38:39], v[34:35]
	s_nop 0
	v_addc_co_u32_e32 v37, vcc, 0, v109, vcc
	v_mov_b32_e32 v38, v52
	v_mov_b32_e32 v39, v56
	v_mov_b32_e32 v56, v53
	global_store_dwordx4 v[36:37], v[32:35], off sc1
	v_pk_mul_f32 v[38:39], v[112:113], v[38:39] op_sel_hi:[0,1]
	v_pk_mul_f32 v[40:41], v[112:113], v[56:57] op_sel_hi:[0,1]
	v_lshlrev_b32_e32 v32, 16, v104
	v_and_b32_e32 v33, 0xffff0000, v104
	v_lshlrev_b32_e32 v34, 16, v105
	v_and_b32_e32 v35, 0xffff0000, v105
	v_pk_fma_f32 v[34:35], v[22:23], v[40:41], v[34:35]
	v_pk_fma_f32 v[32:33], v[20:21], v[38:39], v[32:33]
	global_store_dwordx4 v[36:37], v[32:35], off offset:1024 sc1
	v_pk_mul_f32 v[38:39], v[60:61], v[112:113] op_sel_hi:[1,0]
	v_pk_mul_f32 v[40:41], v[110:111], v[112:113] op_sel_hi:[1,0]
	v_lshlrev_b32_e32 v32, 16, v102
	v_and_b32_e32 v33, 0xffff0000, v102
	v_lshlrev_b32_e32 v34, 16, v103
	v_and_b32_e32 v35, 0xffff0000, v103
	v_pk_fma_f32 v[34:35], v[30:31], v[40:41], v[34:35]
	v_pk_fma_f32 v[32:33], v[28:29], v[38:39], v[32:33]
	global_store_dwordx4 v[36:37], v[32:35], off offset:2048 sc1
	v_pk_mul_f32 v[38:39], v[62:63], v[112:113] op_sel_hi:[1,0]
	v_pk_mul_f32 v[40:41], v[114:115], v[112:113] op_sel_hi:[1,0]
	v_lshlrev_b32_e32 v32, 16, v100
	v_and_b32_e32 v33, 0xffff0000, v100
	v_lshlrev_b32_e32 v34, 16, v101
	v_and_b32_e32 v35, 0xffff0000, v101
	v_pk_fma_f32 v[34:35], v[26:27], v[40:41], v[34:35]
	v_pk_fma_f32 v[32:33], v[24:25], v[38:39], v[32:33]
	global_store_dwordx4 v[36:37], v[32:35], off offset:3072 sc1
	s_branch .LBB0_1320
